# P8 Horner rescale: gate loads software-pipelined 4 row groups deep with counted waits (was 32 serialized round trips)
# speedup vs baseline: 1.0376x; 1.0137x over previous
; __device__ __forceinline__ int fresh_tid() { int t = threadIdx.x; asm volatile("" : "+v"(t)); return t; }
; template <class Epi>
; __device__ __forceinline__ void gemm_phase(LAS unsigned char* lds, const Gemm g, const StaticOrder& S, const Epi& E) {
;     ...
;             if constexpr (Epi::RESCALE) { if (t != 0 && (t & 7) == 0) { const int t2 = fresh_tid(); const int w2 = __builtin_amdgcn_readfirstlane(t2 >> 6); E.rescale(acc, cur, t >> 3, w2 >> 2, w2 & 3, t2 & 15, (t2 >> 4) & 3); } }
;     __device__ __forceinline__ void rescale(AccT& acc, const Unit& u, int k, int wr, int wc, int fr, int fq) const {
;         int row0 = u.pm * 256 + wr * 64 + fr, col0 = u.pn * 256 + wc * 32 + 8 * fq;
;         asm volatile("" : "+v"(row0), "+v"(col0));
; #pragma unroll
;         for (int ai = 0; ai < 2; ++ai)
; #pragma unroll
;             for (int m = 0; m < 4; ++m) { const bf16_t* gp = proj + (size_t)(row0 + ai * 128 + m * 16) * NP + GATE0 + (k - 1) * DM + col0;
; #pragma unroll
;                 for (int bj = 0; bj < 2; ++bj) { float ga[8], gb[8]; ld8(gp + bj * 128, ga); ld8(gp + DM + bj * 128, gb);
;                     f32x4 r0, r1;
; #pragma unroll
;                     for (int e = 0; e < 4; ++e) { r0[e] = ga[e] * __builtin_amdgcn_rcpf(fmaxf(gb[e], 1e-30f)); r1[e] = ga[4 + e] * __builtin_amdgcn_rcpf(fmaxf(gb[4 + e], 1e-30f)); }
;                     acc[ai][bj][m][0] = acc[ai][bj][m][0] * r0; acc[ai][bj][m][1] = acc[ai][bj][m][1] * r1; }
.LBB0_1379:
	s_add_i32 s93, s93, 2
	s_cmp_eq_u32 s42, 0
	s_cselect_b64 s[6:7], -1, 0
	s_and_b32 s20, s93, 6
	s_cmp_lg_u32 s20, 0
	s_cselect_b64 s[20:21], -1, 0
	s_or_b64 s[6:7], s[6:7], s[20:21]
	s_and_b64 vcc, exec, s[6:7]
	s_cbranch_vccnz .LBB0_1378
	v_mov_b32_e32 v2, v250
	s_nop 0
	v_readfirstlane_b32 s6, v2
	s_ashr_i32 s7, s6, 2
	s_andn2_b32 s7, s7, 63
	s_add_i32 s7, s7, s31
	s_lshr_b32 s6, s6, 1
	v_and_or_b32 v0, v2, 15, s7
	s_and_b32 s6, s6, 0x60
	v_lshrrev_b32_e32 v2, 1, v2
	v_and_or_b32 v2, v2, 24, s6
	v_or_b32_e32 v2, s30, v2
	s_add_u32 s34, s0, s42
	v_ashrrev_i32_e32 v3, 31, v2
	v_lshlrev_b64 v[2:3], 1, v[2:3]
	v_mad_i64_i32 v[132:133], s[6:7], v0, s26, v[2:3]
	s_addc_u32 s35, s1, s43
	v_mov_b32_e32 v2, v132
	s_add_u32 s6, s34, s78
	s_addc_u32 s7, s35, 0
	s_add_u32 s20, s34, s13
	s_addc_u32 s21, s35, 0
	global_load_dwordx4 v[164:167], v2, s[6:7] offset:2560
	global_load_dwordx4 v[168:171], v2, s[6:7] offset:2816
	global_load_dwordx4 v[172:175], v2, s[20:21] offset:2560
	global_load_dwordx4 v[176:179], v2, s[20:21] offset:2816
	s_add_u32 s6, s6, 0x8a000
	s_addc_u32 s7, s7, 0
	s_add_u32 s20, s20, 0x8a000
	s_addc_u32 s21, s21, 0
	global_load_dwordx4 v[188:191], v2, s[6:7] offset:2560
	global_load_dwordx4 v[192:195], v2, s[6:7] offset:2816
	global_load_dwordx4 v[196:199], v2, s[20:21] offset:2560
	global_load_dwordx4 v[200:203], v2, s[20:21] offset:2816
	s_add_u32 s6, s6, 0x8a000
	s_addc_u32 s7, s7, 0
	s_add_u32 s20, s20, 0x8a000
	s_addc_u32 s21, s21, 0
	global_load_dwordx4 v[206:209], v2, s[6:7] offset:2560
	global_load_dwordx4 v[210:213], v2, s[6:7] offset:2816
	global_load_dwordx4 v[214:217], v2, s[20:21] offset:2560
	global_load_dwordx4 v[218:221], v2, s[20:21] offset:2816
	s_add_u32 s6, s6, 0x8a000
	s_addc_u32 s7, s7, 0
	s_add_u32 s20, s20, 0x8a000
	s_addc_u32 s21, s21, 0
	global_load_dwordx4 v[226:229], v2, s[6:7] offset:2560
	global_load_dwordx4 v[230:233], v2, s[6:7] offset:2816
	global_load_dwordx4 v[234:237], v2, s[20:21] offset:2560
	global_load_dwordx4 v[238:241], v2, s[20:21] offset:2816
	s_add_u32 s6, s6, 0x2b2000
	s_addc_u32 s7, s7, 0
	s_add_u32 s20, s20, 0x2b2000
	s_addc_u32 s21, s21, 0
	s_waitcnt vmcnt(12)
	v_and_b32_e32 v133, 0xffff0000, v172
	v_lshlrev_b32_e32 v132, 16, v172
	v_and_b32_e32 v135, 0xffff0000, v173
	v_lshlrev_b32_e32 v134, 16, v173
	v_and_b32_e32 v137, 0xffff0000, v174
	v_lshlrev_b32_e32 v136, 16, v174
	v_and_b32_e32 v139, 0xffff0000, v175
	v_lshlrev_b32_e32 v138, 16, v175
	v_max_f32_e32 v132, 0xda24260, v132
	v_max_f32_e32 v133, 0xda24260, v133
	v_max_f32_e32 v134, 0xda24260, v134
	v_max_f32_e32 v135, 0xda24260, v135
	v_max_f32_e32 v136, 0xda24260, v136
	v_max_f32_e32 v137, 0xda24260, v137
	v_max_f32_e32 v138, 0xda24260, v138
	v_max_f32_e32 v139, 0xda24260, v139
	v_rcp_f32_e32 v132, v132
	v_rcp_f32_e32 v133, v133
	v_rcp_f32_e32 v134, v134
	v_rcp_f32_e32 v135, v135
	v_rcp_f32_e32 v136, v136
	v_rcp_f32_e32 v137, v137
	v_rcp_f32_e32 v138, v138
	v_rcp_f32_e32 v139, v139
	v_and_b32_e32 v147, 0xffff0000, v164
	v_lshlrev_b32_e32 v146, 16, v164
	v_and_b32_e32 v149, 0xffff0000, v165
	v_lshlrev_b32_e32 v148, 16, v165
	v_and_b32_e32 v151, 0xffff0000, v166
	v_lshlrev_b32_e32 v150, 16, v166
	v_and_b32_e32 v153, 0xffff0000, v167
	v_lshlrev_b32_e32 v152, 16, v167
	v_pk_mul_f32 v[132:133], v[132:133], v[146:147]
	v_pk_mul_f32 v[134:135], v[134:135], v[148:149]
	v_pk_mul_f32 v[136:137], v[136:137], v[150:151]
	v_pk_mul_f32 v[138:139], v[138:139], v[152:153]
	v_pk_mul_f32 v[128:129], v[128:129], v[132:133]
	v_pk_mul_f32 v[130:131], v[130:131], v[134:135]
	v_pk_mul_f32 v[124:125], v[124:125], v[136:137]
	v_pk_mul_f32 v[126:127], v[126:127], v[138:139]
	v_and_b32_e32 v133, 0xffff0000, v176
	v_lshlrev_b32_e32 v132, 16, v176
	v_and_b32_e32 v135, 0xffff0000, v177
	v_lshlrev_b32_e32 v134, 16, v177
	v_and_b32_e32 v137, 0xffff0000, v178
	v_lshlrev_b32_e32 v136, 16, v178
	v_and_b32_e32 v139, 0xffff0000, v179
	v_lshlrev_b32_e32 v138, 16, v179
	v_max_f32_e32 v132, 0xda24260, v132
	v_max_f32_e32 v133, 0xda24260, v133
	v_max_f32_e32 v134, 0xda24260, v134
	v_max_f32_e32 v135, 0xda24260, v135
	v_max_f32_e32 v136, 0xda24260, v136
	v_max_f32_e32 v137, 0xda24260, v137
	v_max_f32_e32 v138, 0xda24260, v138
	v_max_f32_e32 v139, 0xda24260, v139
	v_rcp_f32_e32 v132, v132
	v_rcp_f32_e32 v133, v133
	v_rcp_f32_e32 v134, v134
	v_rcp_f32_e32 v135, v135
	v_rcp_f32_e32 v136, v136
	v_rcp_f32_e32 v137, v137
	v_rcp_f32_e32 v138, v138
	v_rcp_f32_e32 v139, v139
	v_and_b32_e32 v147, 0xffff0000, v168
	v_lshlrev_b32_e32 v146, 16, v168
	v_and_b32_e32 v149, 0xffff0000, v169
	v_lshlrev_b32_e32 v148, 16, v169
	v_and_b32_e32 v151, 0xffff0000, v170
	v_lshlrev_b32_e32 v150, 16, v170
	v_and_b32_e32 v153, 0xffff0000, v171
	v_lshlrev_b32_e32 v152, 16, v171
	v_pk_mul_f32 v[132:133], v[132:133], v[146:147]
	v_pk_mul_f32 v[134:135], v[134:135], v[148:149]
	v_pk_mul_f32 v[136:137], v[136:137], v[150:151]
	v_pk_mul_f32 v[138:139], v[138:139], v[152:153]
	v_pk_mul_f32 v[120:121], v[120:121], v[132:133]
	v_pk_mul_f32 v[122:123], v[122:123], v[134:135]
	v_pk_mul_f32 v[116:117], v[116:117], v[136:137]
	v_pk_mul_f32 v[118:119], v[118:119], v[138:139]
	global_load_dwordx4 v[164:167], v2, s[6:7] offset:2560
	global_load_dwordx4 v[168:171], v2, s[6:7] offset:2816
	global_load_dwordx4 v[172:175], v2, s[20:21] offset:2560
	global_load_dwordx4 v[176:179], v2, s[20:21] offset:2816
	s_add_u32 s6, s6, 0x8a000
	s_addc_u32 s7, s7, 0
	s_add_u32 s20, s20, 0x8a000
	s_addc_u32 s21, s21, 0
	s_waitcnt vmcnt(12)
;     __device__ __forceinline__ void rescale(AccT& acc, const Unit& u, int k, int wr, int wc, int fr, int fq) const {
;     ...
;             for (int m = 0; m < 4; ++m) { const bf16_t* gp = proj + (size_t)(row0 + ai * 128 + m * 16) * NP + GATE0 + (k - 1) * DM + col0;
; #pragma unroll
;                 for (int bj = 0; bj < 2; ++bj) { float ga[8], gb[8]; ld8(gp + bj * 128, ga); ld8(gp + DM + bj * 128, gb);
;                     f32x4 r0, r1;
; #pragma unroll
;                     for (int e = 0; e < 4; ++e) { r0[e] = ga[e] * __builtin_amdgcn_rcpf(fmaxf(gb[e], 1e-30f)); r1[e] = ga[4 + e] * __builtin_amdgcn_rcpf(fmaxf(gb[4 + e], 1e-30f)); }
;                     acc[ai][bj][m][0] = acc[ai][bj][m][0] * r0; acc[ai][bj][m][1] = acc[ai][bj][m][1] * r1; }
	v_and_b32_e32 v133, 0xffff0000, v196
	v_lshlrev_b32_e32 v132, 16, v196
	v_and_b32_e32 v135, 0xffff0000, v197
	v_lshlrev_b32_e32 v134, 16, v197
	v_and_b32_e32 v137, 0xffff0000, v198
	v_lshlrev_b32_e32 v136, 16, v198
	v_and_b32_e32 v139, 0xffff0000, v199
	v_lshlrev_b32_e32 v138, 16, v199
	v_max_f32_e32 v132, 0xda24260, v132
	v_max_f32_e32 v133, 0xda24260, v133
	v_max_f32_e32 v134, 0xda24260, v134
	v_max_f32_e32 v135, 0xda24260, v135
	v_max_f32_e32 v136, 0xda24260, v136
	v_max_f32_e32 v137, 0xda24260, v137
	v_max_f32_e32 v138, 0xda24260, v138
	v_max_f32_e32 v139, 0xda24260, v139
	v_rcp_f32_e32 v132, v132
	v_rcp_f32_e32 v133, v133
	v_rcp_f32_e32 v134, v134
	v_rcp_f32_e32 v135, v135
	v_rcp_f32_e32 v136, v136
	v_rcp_f32_e32 v137, v137
	v_rcp_f32_e32 v138, v138
	v_rcp_f32_e32 v139, v139
	v_and_b32_e32 v147, 0xffff0000, v188
	v_lshlrev_b32_e32 v146, 16, v188
	v_and_b32_e32 v149, 0xffff0000, v189
	v_lshlrev_b32_e32 v148, 16, v189
	v_and_b32_e32 v151, 0xffff0000, v190
	v_lshlrev_b32_e32 v150, 16, v190
	v_and_b32_e32 v153, 0xffff0000, v191
	v_lshlrev_b32_e32 v152, 16, v191
	v_pk_mul_f32 v[132:133], v[132:133], v[146:147]
	v_pk_mul_f32 v[134:135], v[134:135], v[148:149]
	v_pk_mul_f32 v[136:137], v[136:137], v[150:151]
	v_pk_mul_f32 v[138:139], v[138:139], v[152:153]
	v_pk_mul_f32 v[112:113], v[112:113], v[132:133]
	v_pk_mul_f32 v[114:115], v[114:115], v[134:135]
	v_pk_mul_f32 v[108:109], v[108:109], v[136:137]
	v_pk_mul_f32 v[110:111], v[110:111], v[138:139]
	v_and_b32_e32 v133, 0xffff0000, v200
	v_lshlrev_b32_e32 v132, 16, v200
	v_and_b32_e32 v135, 0xffff0000, v201
	v_lshlrev_b32_e32 v134, 16, v201
	v_and_b32_e32 v137, 0xffff0000, v202
	v_lshlrev_b32_e32 v136, 16, v202
	v_and_b32_e32 v139, 0xffff0000, v203
	v_lshlrev_b32_e32 v138, 16, v203
	v_max_f32_e32 v132, 0xda24260, v132
	v_max_f32_e32 v133, 0xda24260, v133
	v_max_f32_e32 v134, 0xda24260, v134
	v_max_f32_e32 v135, 0xda24260, v135
	v_max_f32_e32 v136, 0xda24260, v136
	v_max_f32_e32 v137, 0xda24260, v137
	v_max_f32_e32 v138, 0xda24260, v138
	v_max_f32_e32 v139, 0xda24260, v139
	v_rcp_f32_e32 v132, v132
	v_rcp_f32_e32 v133, v133
	v_rcp_f32_e32 v134, v134
	v_rcp_f32_e32 v135, v135
	v_rcp_f32_e32 v136, v136
	v_rcp_f32_e32 v137, v137
	v_rcp_f32_e32 v138, v138
	v_rcp_f32_e32 v139, v139
	v_and_b32_e32 v147, 0xffff0000, v192
	v_lshlrev_b32_e32 v146, 16, v192
	v_and_b32_e32 v149, 0xffff0000, v193
	v_lshlrev_b32_e32 v148, 16, v193
	v_and_b32_e32 v151, 0xffff0000, v194
	v_lshlrev_b32_e32 v150, 16, v194
	v_and_b32_e32 v153, 0xffff0000, v195
	v_lshlrev_b32_e32 v152, 16, v195
	v_pk_mul_f32 v[132:133], v[132:133], v[146:147]
	v_pk_mul_f32 v[134:135], v[134:135], v[148:149]
	v_pk_mul_f32 v[136:137], v[136:137], v[150:151]
	v_pk_mul_f32 v[138:139], v[138:139], v[152:153]
	v_pk_mul_f32 v[104:105], v[104:105], v[132:133]
	v_pk_mul_f32 v[106:107], v[106:107], v[134:135]
	v_pk_mul_f32 v[100:101], v[100:101], v[136:137]
	v_pk_mul_f32 v[102:103], v[102:103], v[138:139]
	global_load_dwordx4 v[188:191], v2, s[6:7] offset:2560
	global_load_dwordx4 v[192:195], v2, s[6:7] offset:2816
	global_load_dwordx4 v[196:199], v2, s[20:21] offset:2560
	global_load_dwordx4 v[200:203], v2, s[20:21] offset:2816
	s_add_u32 s6, s6, 0x8a000
	s_addc_u32 s7, s7, 0
	s_add_u32 s20, s20, 0x8a000
	s_addc_u32 s21, s21, 0
	s_waitcnt vmcnt(12)
	v_and_b32_e32 v133, 0xffff0000, v214
	v_lshlrev_b32_e32 v132, 16, v214
	v_and_b32_e32 v135, 0xffff0000, v215
	v_lshlrev_b32_e32 v134, 16, v215
	v_and_b32_e32 v137, 0xffff0000, v216
	v_lshlrev_b32_e32 v136, 16, v216
	v_and_b32_e32 v139, 0xffff0000, v217
	v_lshlrev_b32_e32 v138, 16, v217
	v_max_f32_e32 v132, 0xda24260, v132
	v_max_f32_e32 v133, 0xda24260, v133
	v_max_f32_e32 v134, 0xda24260, v134
	v_max_f32_e32 v135, 0xda24260, v135
	v_max_f32_e32 v136, 0xda24260, v136
	v_max_f32_e32 v137, 0xda24260, v137
	v_max_f32_e32 v138, 0xda24260, v138
	v_max_f32_e32 v139, 0xda24260, v139
	v_rcp_f32_e32 v132, v132
	v_rcp_f32_e32 v133, v133
	v_rcp_f32_e32 v134, v134
	v_rcp_f32_e32 v135, v135
	v_rcp_f32_e32 v136, v136
	v_rcp_f32_e32 v137, v137
	v_rcp_f32_e32 v138, v138
	v_rcp_f32_e32 v139, v139
	v_and_b32_e32 v147, 0xffff0000, v206
	v_lshlrev_b32_e32 v146, 16, v206
	v_and_b32_e32 v149, 0xffff0000, v207
	v_lshlrev_b32_e32 v148, 16, v207
	v_and_b32_e32 v151, 0xffff0000, v208
	v_lshlrev_b32_e32 v150, 16, v208
	v_and_b32_e32 v153, 0xffff0000, v209
	v_lshlrev_b32_e32 v152, 16, v209
	v_pk_mul_f32 v[132:133], v[132:133], v[146:147]
	v_pk_mul_f32 v[134:135], v[134:135], v[148:149]
	v_pk_mul_f32 v[136:137], v[136:137], v[150:151]
	v_pk_mul_f32 v[138:139], v[138:139], v[152:153]
	v_pk_mul_f32 v[96:97], v[96:97], v[132:133]
	v_pk_mul_f32 v[98:99], v[98:99], v[134:135]
	v_pk_mul_f32 v[92:93], v[92:93], v[136:137]
	v_pk_mul_f32 v[94:95], v[94:95], v[138:139]
	v_and_b32_e32 v133, 0xffff0000, v218
	v_lshlrev_b32_e32 v132, 16, v218
	v_and_b32_e32 v135, 0xffff0000, v219
	v_lshlrev_b32_e32 v134, 16, v219
	v_and_b32_e32 v137, 0xffff0000, v220
	v_lshlrev_b32_e32 v136, 16, v220
	v_and_b32_e32 v139, 0xffff0000, v221
	v_lshlrev_b32_e32 v138, 16, v221
	v_max_f32_e32 v132, 0xda24260, v132
	v_max_f32_e32 v133, 0xda24260, v133
	v_max_f32_e32 v134, 0xda24260, v134
	v_max_f32_e32 v135, 0xda24260, v135
	v_max_f32_e32 v136, 0xda24260, v136
	v_max_f32_e32 v137, 0xda24260, v137
	v_max_f32_e32 v138, 0xda24260, v138
	v_max_f32_e32 v139, 0xda24260, v139
	v_rcp_f32_e32 v132, v132
	v_rcp_f32_e32 v133, v133
	v_rcp_f32_e32 v134, v134
	v_rcp_f32_e32 v135, v135
	v_rcp_f32_e32 v136, v136
	v_rcp_f32_e32 v137, v137
	v_rcp_f32_e32 v138, v138
	v_rcp_f32_e32 v139, v139
	v_and_b32_e32 v147, 0xffff0000, v210
	v_lshlrev_b32_e32 v146, 16, v210
	v_and_b32_e32 v149, 0xffff0000, v211
	v_lshlrev_b32_e32 v148, 16, v211
	v_and_b32_e32 v151, 0xffff0000, v212
	v_lshlrev_b32_e32 v150, 16, v212
	v_and_b32_e32 v153, 0xffff0000, v213
	v_lshlrev_b32_e32 v152, 16, v213
	v_pk_mul_f32 v[132:133], v[132:133], v[146:147]
	v_pk_mul_f32 v[134:135], v[134:135], v[148:149]
	v_pk_mul_f32 v[136:137], v[136:137], v[150:151]
	v_pk_mul_f32 v[138:139], v[138:139], v[152:153]
	v_pk_mul_f32 v[88:89], v[88:89], v[132:133]
	v_pk_mul_f32 v[90:91], v[90:91], v[134:135]
	v_pk_mul_f32 v[84:85], v[84:85], v[136:137]
	v_pk_mul_f32 v[86:87], v[86:87], v[138:139]
	global_load_dwordx4 v[206:209], v2, s[6:7] offset:2560
	global_load_dwordx4 v[210:213], v2, s[6:7] offset:2816
	global_load_dwordx4 v[214:217], v2, s[20:21] offset:2560
	global_load_dwordx4 v[218:221], v2, s[20:21] offset:2816
	s_add_u32 s6, s6, 0x8a000
	s_addc_u32 s7, s7, 0
	s_add_u32 s20, s20, 0x8a000
	s_addc_u32 s21, s21, 0
	s_waitcnt vmcnt(12)
;     __device__ __forceinline__ void rescale(AccT& acc, const Unit& u, int k, int wr, int wc, int fr, int fq) const {
;     ...
;             for (int m = 0; m < 4; ++m) { const bf16_t* gp = proj + (size_t)(row0 + ai * 128 + m * 16) * NP + GATE0 + (k - 1) * DM + col0;
; #pragma unroll
;                 for (int bj = 0; bj < 2; ++bj) { float ga[8], gb[8]; ld8(gp + bj * 128, ga); ld8(gp + DM + bj * 128, gb);
;                     f32x4 r0, r1;
; #pragma unroll
;                     for (int e = 0; e < 4; ++e) { r0[e] = ga[e] * __builtin_amdgcn_rcpf(fmaxf(gb[e], 1e-30f)); r1[e] = ga[4 + e] * __builtin_amdgcn_rcpf(fmaxf(gb[4 + e], 1e-30f)); }
;                     acc[ai][bj][m][0] = acc[ai][bj][m][0] * r0; acc[ai][bj][m][1] = acc[ai][bj][m][1] * r1; }
	v_and_b32_e32 v133, 0xffff0000, v234
	v_lshlrev_b32_e32 v132, 16, v234
	v_and_b32_e32 v135, 0xffff0000, v235
	v_lshlrev_b32_e32 v134, 16, v235
	v_and_b32_e32 v137, 0xffff0000, v236
	v_lshlrev_b32_e32 v136, 16, v236
	v_and_b32_e32 v139, 0xffff0000, v237
	v_lshlrev_b32_e32 v138, 16, v237
	v_max_f32_e32 v132, 0xda24260, v132
	v_max_f32_e32 v133, 0xda24260, v133
	v_max_f32_e32 v134, 0xda24260, v134
	v_max_f32_e32 v135, 0xda24260, v135
	v_max_f32_e32 v136, 0xda24260, v136
	v_max_f32_e32 v137, 0xda24260, v137
	v_max_f32_e32 v138, 0xda24260, v138
	v_max_f32_e32 v139, 0xda24260, v139
	v_rcp_f32_e32 v132, v132
	v_rcp_f32_e32 v133, v133
	v_rcp_f32_e32 v134, v134
	v_rcp_f32_e32 v135, v135
	v_rcp_f32_e32 v136, v136
	v_rcp_f32_e32 v137, v137
	v_rcp_f32_e32 v138, v138
	v_rcp_f32_e32 v139, v139
	v_and_b32_e32 v147, 0xffff0000, v226
	v_lshlrev_b32_e32 v146, 16, v226
	v_and_b32_e32 v149, 0xffff0000, v227
	v_lshlrev_b32_e32 v148, 16, v227
	v_and_b32_e32 v151, 0xffff0000, v228
	v_lshlrev_b32_e32 v150, 16, v228
	v_and_b32_e32 v153, 0xffff0000, v229
	v_lshlrev_b32_e32 v152, 16, v229
	v_pk_mul_f32 v[132:133], v[132:133], v[146:147]
	v_pk_mul_f32 v[134:135], v[134:135], v[148:149]
	v_pk_mul_f32 v[136:137], v[136:137], v[150:151]
	v_pk_mul_f32 v[138:139], v[138:139], v[152:153]
	v_pk_mul_f32 v[80:81], v[80:81], v[132:133]
	v_pk_mul_f32 v[82:83], v[82:83], v[134:135]
	v_pk_mul_f32 v[76:77], v[76:77], v[136:137]
	v_pk_mul_f32 v[78:79], v[78:79], v[138:139]
	v_and_b32_e32 v133, 0xffff0000, v238
	v_lshlrev_b32_e32 v132, 16, v238
	v_and_b32_e32 v135, 0xffff0000, v239
	v_lshlrev_b32_e32 v134, 16, v239
	v_and_b32_e32 v137, 0xffff0000, v240
	v_lshlrev_b32_e32 v136, 16, v240
	v_and_b32_e32 v139, 0xffff0000, v241
	v_lshlrev_b32_e32 v138, 16, v241
	v_max_f32_e32 v132, 0xda24260, v132
	v_max_f32_e32 v133, 0xda24260, v133
	v_max_f32_e32 v134, 0xda24260, v134
	v_max_f32_e32 v135, 0xda24260, v135
	v_max_f32_e32 v136, 0xda24260, v136
	v_max_f32_e32 v137, 0xda24260, v137
	v_max_f32_e32 v138, 0xda24260, v138
	v_max_f32_e32 v139, 0xda24260, v139
	v_rcp_f32_e32 v132, v132
	v_rcp_f32_e32 v133, v133
	v_rcp_f32_e32 v134, v134
	v_rcp_f32_e32 v135, v135
	v_rcp_f32_e32 v136, v136
	v_rcp_f32_e32 v137, v137
	v_rcp_f32_e32 v138, v138
	v_rcp_f32_e32 v139, v139
	v_and_b32_e32 v147, 0xffff0000, v230
	v_lshlrev_b32_e32 v146, 16, v230
	v_and_b32_e32 v149, 0xffff0000, v231
	v_lshlrev_b32_e32 v148, 16, v231
	v_and_b32_e32 v151, 0xffff0000, v232
	v_lshlrev_b32_e32 v150, 16, v232
	v_and_b32_e32 v153, 0xffff0000, v233
	v_lshlrev_b32_e32 v152, 16, v233
	v_pk_mul_f32 v[132:133], v[132:133], v[146:147]
	v_pk_mul_f32 v[134:135], v[134:135], v[148:149]
	v_pk_mul_f32 v[136:137], v[136:137], v[150:151]
	v_pk_mul_f32 v[138:139], v[138:139], v[152:153]
	v_pk_mul_f32 v[72:73], v[72:73], v[132:133]
	v_pk_mul_f32 v[74:75], v[74:75], v[134:135]
	v_pk_mul_f32 v[68:69], v[68:69], v[136:137]
	v_pk_mul_f32 v[70:71], v[70:71], v[138:139]
	global_load_dwordx4 v[226:229], v2, s[6:7] offset:2560
	global_load_dwordx4 v[230:233], v2, s[6:7] offset:2816
	global_load_dwordx4 v[234:237], v2, s[20:21] offset:2560
	global_load_dwordx4 v[238:241], v2, s[20:21] offset:2816
	s_waitcnt vmcnt(12)
	v_and_b32_e32 v133, 0xffff0000, v172
	v_lshlrev_b32_e32 v132, 16, v172
	v_and_b32_e32 v135, 0xffff0000, v173
	v_lshlrev_b32_e32 v134, 16, v173
	v_and_b32_e32 v137, 0xffff0000, v174
	v_lshlrev_b32_e32 v136, 16, v174
	v_and_b32_e32 v139, 0xffff0000, v175
	v_lshlrev_b32_e32 v138, 16, v175
	v_max_f32_e32 v132, 0xda24260, v132
	v_max_f32_e32 v133, 0xda24260, v133
	v_max_f32_e32 v134, 0xda24260, v134
	v_max_f32_e32 v135, 0xda24260, v135
	v_max_f32_e32 v136, 0xda24260, v136
	v_max_f32_e32 v137, 0xda24260, v137
	v_max_f32_e32 v138, 0xda24260, v138
	v_max_f32_e32 v139, 0xda24260, v139
	v_rcp_f32_e32 v132, v132
	v_rcp_f32_e32 v133, v133
	v_rcp_f32_e32 v134, v134
	v_rcp_f32_e32 v135, v135
	v_rcp_f32_e32 v136, v136
	v_rcp_f32_e32 v137, v137
	v_rcp_f32_e32 v138, v138
	v_rcp_f32_e32 v139, v139
	v_and_b32_e32 v147, 0xffff0000, v164
	v_lshlrev_b32_e32 v146, 16, v164
	v_and_b32_e32 v149, 0xffff0000, v165
	v_lshlrev_b32_e32 v148, 16, v165
	v_and_b32_e32 v151, 0xffff0000, v166
	v_lshlrev_b32_e32 v150, 16, v166
	v_and_b32_e32 v153, 0xffff0000, v167
	v_lshlrev_b32_e32 v152, 16, v167
	v_pk_mul_f32 v[132:133], v[132:133], v[146:147]
	v_pk_mul_f32 v[134:135], v[134:135], v[148:149]
	v_pk_mul_f32 v[136:137], v[136:137], v[150:151]
	v_pk_mul_f32 v[138:139], v[138:139], v[152:153]
	v_pk_mul_f32 v[64:65], v[64:65], v[132:133]
	v_pk_mul_f32 v[66:67], v[66:67], v[134:135]
	v_pk_mul_f32 v[60:61], v[60:61], v[136:137]
	v_pk_mul_f32 v[62:63], v[62:63], v[138:139]
	v_and_b32_e32 v133, 0xffff0000, v176
	v_lshlrev_b32_e32 v132, 16, v176
	v_and_b32_e32 v135, 0xffff0000, v177
	v_lshlrev_b32_e32 v134, 16, v177
	v_and_b32_e32 v137, 0xffff0000, v178
	v_lshlrev_b32_e32 v136, 16, v178
	v_and_b32_e32 v139, 0xffff0000, v179
	v_lshlrev_b32_e32 v138, 16, v179
	v_max_f32_e32 v132, 0xda24260, v132
	v_max_f32_e32 v133, 0xda24260, v133
	v_max_f32_e32 v134, 0xda24260, v134
	v_max_f32_e32 v135, 0xda24260, v135
	v_max_f32_e32 v136, 0xda24260, v136
	v_max_f32_e32 v137, 0xda24260, v137
	v_max_f32_e32 v138, 0xda24260, v138
	v_max_f32_e32 v139, 0xda24260, v139
	v_rcp_f32_e32 v132, v132
	v_rcp_f32_e32 v133, v133
	v_rcp_f32_e32 v134, v134
	v_rcp_f32_e32 v135, v135
	v_rcp_f32_e32 v136, v136
	v_rcp_f32_e32 v137, v137
	v_rcp_f32_e32 v138, v138
	v_rcp_f32_e32 v139, v139
	v_and_b32_e32 v147, 0xffff0000, v168
	v_lshlrev_b32_e32 v146, 16, v168
	v_and_b32_e32 v149, 0xffff0000, v169
	v_lshlrev_b32_e32 v148, 16, v169
	v_and_b32_e32 v151, 0xffff0000, v170
	v_lshlrev_b32_e32 v150, 16, v170
	v_and_b32_e32 v153, 0xffff0000, v171
	v_lshlrev_b32_e32 v152, 16, v171
	v_pk_mul_f32 v[132:133], v[132:133], v[146:147]
	v_pk_mul_f32 v[134:135], v[134:135], v[148:149]
	v_pk_mul_f32 v[136:137], v[136:137], v[150:151]
	v_pk_mul_f32 v[138:139], v[138:139], v[152:153]
	v_pk_mul_f32 v[56:57], v[56:57], v[132:133]
	v_pk_mul_f32 v[58:59], v[58:59], v[134:135]
	v_pk_mul_f32 v[52:53], v[52:53], v[136:137]
	v_pk_mul_f32 v[54:55], v[54:55], v[138:139]
	s_waitcnt vmcnt(8)
;     __device__ __forceinline__ void rescale(AccT& acc, const Unit& u, int k, int wr, int wc, int fr, int fq) const {
;     ...
;             for (int m = 0; m < 4; ++m) { const bf16_t* gp = proj + (size_t)(row0 + ai * 128 + m * 16) * NP + GATE0 + (k - 1) * DM + col0;
; #pragma unroll
;                 for (int bj = 0; bj < 2; ++bj) { float ga[8], gb[8]; ld8(gp + bj * 128, ga); ld8(gp + DM + bj * 128, gb);
;                     f32x4 r0, r1;
; #pragma unroll
;                     for (int e = 0; e < 4; ++e) { r0[e] = ga[e] * __builtin_amdgcn_rcpf(fmaxf(gb[e], 1e-30f)); r1[e] = ga[4 + e] * __builtin_amdgcn_rcpf(fmaxf(gb[4 + e], 1e-30f)); }
;                     acc[ai][bj][m][0] = acc[ai][bj][m][0] * r0; acc[ai][bj][m][1] = acc[ai][bj][m][1] * r1; }
	v_and_b32_e32 v133, 0xffff0000, v196
	v_lshlrev_b32_e32 v132, 16, v196
	v_and_b32_e32 v135, 0xffff0000, v197
	v_lshlrev_b32_e32 v134, 16, v197
	v_and_b32_e32 v137, 0xffff0000, v198
	v_lshlrev_b32_e32 v136, 16, v198
	v_and_b32_e32 v139, 0xffff0000, v199
	v_lshlrev_b32_e32 v138, 16, v199
	v_max_f32_e32 v132, 0xda24260, v132
	v_max_f32_e32 v133, 0xda24260, v133
	v_max_f32_e32 v134, 0xda24260, v134
	v_max_f32_e32 v135, 0xda24260, v135
	v_max_f32_e32 v136, 0xda24260, v136
	v_max_f32_e32 v137, 0xda24260, v137
	v_max_f32_e32 v138, 0xda24260, v138
	v_max_f32_e32 v139, 0xda24260, v139
	v_rcp_f32_e32 v132, v132
	v_rcp_f32_e32 v133, v133
	v_rcp_f32_e32 v134, v134
	v_rcp_f32_e32 v135, v135
	v_rcp_f32_e32 v136, v136
	v_rcp_f32_e32 v137, v137
	v_rcp_f32_e32 v138, v138
	v_rcp_f32_e32 v139, v139
	v_and_b32_e32 v147, 0xffff0000, v188
	v_lshlrev_b32_e32 v146, 16, v188
	v_and_b32_e32 v149, 0xffff0000, v189
	v_lshlrev_b32_e32 v148, 16, v189
	v_and_b32_e32 v151, 0xffff0000, v190
	v_lshlrev_b32_e32 v150, 16, v190
	v_and_b32_e32 v153, 0xffff0000, v191
	v_lshlrev_b32_e32 v152, 16, v191
	v_pk_mul_f32 v[132:133], v[132:133], v[146:147]
	v_pk_mul_f32 v[134:135], v[134:135], v[148:149]
	v_pk_mul_f32 v[136:137], v[136:137], v[150:151]
	v_pk_mul_f32 v[138:139], v[138:139], v[152:153]
	v_pk_mul_f32 v[48:49], v[48:49], v[132:133]
	v_pk_mul_f32 v[50:51], v[50:51], v[134:135]
	v_pk_mul_f32 v[44:45], v[44:45], v[136:137]
	v_pk_mul_f32 v[46:47], v[46:47], v[138:139]
	v_and_b32_e32 v133, 0xffff0000, v200
	v_lshlrev_b32_e32 v132, 16, v200
	v_and_b32_e32 v135, 0xffff0000, v201
	v_lshlrev_b32_e32 v134, 16, v201
	v_and_b32_e32 v137, 0xffff0000, v202
	v_lshlrev_b32_e32 v136, 16, v202
	v_and_b32_e32 v139, 0xffff0000, v203
	v_lshlrev_b32_e32 v138, 16, v203
	v_max_f32_e32 v132, 0xda24260, v132
	v_max_f32_e32 v133, 0xda24260, v133
	v_max_f32_e32 v134, 0xda24260, v134
	v_max_f32_e32 v135, 0xda24260, v135
	v_max_f32_e32 v136, 0xda24260, v136
	v_max_f32_e32 v137, 0xda24260, v137
	v_max_f32_e32 v138, 0xda24260, v138
	v_max_f32_e32 v139, 0xda24260, v139
	v_rcp_f32_e32 v132, v132
	v_rcp_f32_e32 v133, v133
	v_rcp_f32_e32 v134, v134
	v_rcp_f32_e32 v135, v135
	v_rcp_f32_e32 v136, v136
	v_rcp_f32_e32 v137, v137
	v_rcp_f32_e32 v138, v138
	v_rcp_f32_e32 v139, v139
	v_and_b32_e32 v147, 0xffff0000, v192
	v_lshlrev_b32_e32 v146, 16, v192
	v_and_b32_e32 v149, 0xffff0000, v193
	v_lshlrev_b32_e32 v148, 16, v193
	v_and_b32_e32 v151, 0xffff0000, v194
	v_lshlrev_b32_e32 v150, 16, v194
	v_and_b32_e32 v153, 0xffff0000, v195
	v_lshlrev_b32_e32 v152, 16, v195
	v_pk_mul_f32 v[132:133], v[132:133], v[146:147]
	v_pk_mul_f32 v[134:135], v[134:135], v[148:149]
	v_pk_mul_f32 v[136:137], v[136:137], v[150:151]
	v_pk_mul_f32 v[138:139], v[138:139], v[152:153]
	v_pk_mul_f32 v[40:41], v[40:41], v[132:133]
	v_pk_mul_f32 v[42:43], v[42:43], v[134:135]
	v_pk_mul_f32 v[36:37], v[36:37], v[136:137]
	v_pk_mul_f32 v[38:39], v[38:39], v[138:139]
	s_waitcnt vmcnt(4)
;     __device__ __forceinline__ void rescale(AccT& acc, const Unit& u, int k, int wr, int wc, int fr, int fq) const {
;     ...
;             for (int m = 0; m < 4; ++m) { const bf16_t* gp = proj + (size_t)(row0 + ai * 128 + m * 16) * NP + GATE0 + (k - 1) * DM + col0;
; #pragma unroll
;                 for (int bj = 0; bj < 2; ++bj) { float ga[8], gb[8]; ld8(gp + bj * 128, ga); ld8(gp + DM + bj * 128, gb);
;                     f32x4 r0, r1;
; #pragma unroll
;                     for (int e = 0; e < 4; ++e) { r0[e] = ga[e] * __builtin_amdgcn_rcpf(fmaxf(gb[e], 1e-30f)); r1[e] = ga[4 + e] * __builtin_amdgcn_rcpf(fmaxf(gb[4 + e], 1e-30f)); }
;                     acc[ai][bj][m][0] = acc[ai][bj][m][0] * r0; acc[ai][bj][m][1] = acc[ai][bj][m][1] * r1; }
	v_and_b32_e32 v133, 0xffff0000, v214
	v_lshlrev_b32_e32 v132, 16, v214
	v_and_b32_e32 v135, 0xffff0000, v215
	v_lshlrev_b32_e32 v134, 16, v215
	v_and_b32_e32 v137, 0xffff0000, v216
	v_lshlrev_b32_e32 v136, 16, v216
	v_and_b32_e32 v139, 0xffff0000, v217
	v_lshlrev_b32_e32 v138, 16, v217
	v_max_f32_e32 v132, 0xda24260, v132
	v_max_f32_e32 v133, 0xda24260, v133
	v_max_f32_e32 v134, 0xda24260, v134
	v_max_f32_e32 v135, 0xda24260, v135
	v_max_f32_e32 v136, 0xda24260, v136
	v_max_f32_e32 v137, 0xda24260, v137
	v_max_f32_e32 v138, 0xda24260, v138
	v_max_f32_e32 v139, 0xda24260, v139
	v_rcp_f32_e32 v132, v132
	v_rcp_f32_e32 v133, v133
	v_rcp_f32_e32 v134, v134
	v_rcp_f32_e32 v135, v135
	v_rcp_f32_e32 v136, v136
	v_rcp_f32_e32 v137, v137
	v_rcp_f32_e32 v138, v138
	v_rcp_f32_e32 v139, v139
	v_and_b32_e32 v147, 0xffff0000, v206
	v_lshlrev_b32_e32 v146, 16, v206
	v_and_b32_e32 v149, 0xffff0000, v207
	v_lshlrev_b32_e32 v148, 16, v207
	v_and_b32_e32 v151, 0xffff0000, v208
	v_lshlrev_b32_e32 v150, 16, v208
	v_and_b32_e32 v153, 0xffff0000, v209
	v_lshlrev_b32_e32 v152, 16, v209
	v_pk_mul_f32 v[132:133], v[132:133], v[146:147]
	v_pk_mul_f32 v[134:135], v[134:135], v[148:149]
	v_pk_mul_f32 v[136:137], v[136:137], v[150:151]
	v_pk_mul_f32 v[138:139], v[138:139], v[152:153]
	v_pk_mul_f32 v[32:33], v[32:33], v[132:133]
	v_pk_mul_f32 v[34:35], v[34:35], v[134:135]
	v_pk_mul_f32 v[28:29], v[28:29], v[136:137]
	v_pk_mul_f32 v[30:31], v[30:31], v[138:139]
	v_and_b32_e32 v133, 0xffff0000, v218
	v_lshlrev_b32_e32 v132, 16, v218
	v_and_b32_e32 v135, 0xffff0000, v219
	v_lshlrev_b32_e32 v134, 16, v219
	v_and_b32_e32 v137, 0xffff0000, v220
	v_lshlrev_b32_e32 v136, 16, v220
	v_and_b32_e32 v139, 0xffff0000, v221
	v_lshlrev_b32_e32 v138, 16, v221
	v_max_f32_e32 v132, 0xda24260, v132
	v_max_f32_e32 v133, 0xda24260, v133
	v_max_f32_e32 v134, 0xda24260, v134
	v_max_f32_e32 v135, 0xda24260, v135
	v_max_f32_e32 v136, 0xda24260, v136
	v_max_f32_e32 v137, 0xda24260, v137
	v_max_f32_e32 v138, 0xda24260, v138
	v_max_f32_e32 v139, 0xda24260, v139
	v_rcp_f32_e32 v132, v132
	v_rcp_f32_e32 v133, v133
	v_rcp_f32_e32 v134, v134
	v_rcp_f32_e32 v135, v135
	v_rcp_f32_e32 v136, v136
	v_rcp_f32_e32 v137, v137
	v_rcp_f32_e32 v138, v138
	v_rcp_f32_e32 v139, v139
	v_and_b32_e32 v147, 0xffff0000, v210
	v_lshlrev_b32_e32 v146, 16, v210
	v_and_b32_e32 v149, 0xffff0000, v211
	v_lshlrev_b32_e32 v148, 16, v211
	v_and_b32_e32 v151, 0xffff0000, v212
	v_lshlrev_b32_e32 v150, 16, v212
	v_and_b32_e32 v153, 0xffff0000, v213
	v_lshlrev_b32_e32 v152, 16, v213
	v_pk_mul_f32 v[132:133], v[132:133], v[146:147]
	v_pk_mul_f32 v[134:135], v[134:135], v[148:149]
	v_pk_mul_f32 v[136:137], v[136:137], v[150:151]
	v_pk_mul_f32 v[138:139], v[138:139], v[152:153]
	v_pk_mul_f32 v[24:25], v[24:25], v[132:133]
	v_pk_mul_f32 v[26:27], v[26:27], v[134:135]
	v_pk_mul_f32 v[20:21], v[20:21], v[136:137]
	v_pk_mul_f32 v[22:23], v[22:23], v[138:139]
	s_waitcnt vmcnt(0)
	v_and_b32_e32 v133, 0xffff0000, v234
	v_lshlrev_b32_e32 v132, 16, v234
	v_and_b32_e32 v135, 0xffff0000, v235
	v_lshlrev_b32_e32 v134, 16, v235
	v_and_b32_e32 v137, 0xffff0000, v236
	v_lshlrev_b32_e32 v136, 16, v236
	v_and_b32_e32 v139, 0xffff0000, v237
	v_lshlrev_b32_e32 v138, 16, v237
	v_max_f32_e32 v132, 0xda24260, v132
	v_max_f32_e32 v133, 0xda24260, v133
	v_max_f32_e32 v134, 0xda24260, v134
	v_max_f32_e32 v135, 0xda24260, v135
	v_max_f32_e32 v136, 0xda24260, v136
	v_max_f32_e32 v137, 0xda24260, v137
	v_max_f32_e32 v138, 0xda24260, v138
	v_max_f32_e32 v139, 0xda24260, v139
	v_rcp_f32_e32 v132, v132
	v_rcp_f32_e32 v133, v133
	v_rcp_f32_e32 v134, v134
	v_rcp_f32_e32 v135, v135
	v_rcp_f32_e32 v136, v136
	v_rcp_f32_e32 v137, v137
	v_rcp_f32_e32 v138, v138
	v_rcp_f32_e32 v139, v139
	v_and_b32_e32 v147, 0xffff0000, v226
	v_lshlrev_b32_e32 v146, 16, v226
	v_and_b32_e32 v149, 0xffff0000, v227
	v_lshlrev_b32_e32 v148, 16, v227
	v_and_b32_e32 v151, 0xffff0000, v228
	v_lshlrev_b32_e32 v150, 16, v228
	v_and_b32_e32 v153, 0xffff0000, v229
	v_lshlrev_b32_e32 v152, 16, v229
	v_pk_mul_f32 v[132:133], v[132:133], v[146:147]
	v_pk_mul_f32 v[134:135], v[134:135], v[148:149]
	v_pk_mul_f32 v[136:137], v[136:137], v[150:151]
	v_pk_mul_f32 v[138:139], v[138:139], v[152:153]
	v_pk_mul_f32 v[16:17], v[16:17], v[132:133]
	v_pk_mul_f32 v[18:19], v[18:19], v[134:135]
	v_pk_mul_f32 v[12:13], v[12:13], v[136:137]
	v_pk_mul_f32 v[14:15], v[14:15], v[138:139]
	v_and_b32_e32 v133, 0xffff0000, v238
	v_lshlrev_b32_e32 v132, 16, v238
	v_and_b32_e32 v135, 0xffff0000, v239
	v_lshlrev_b32_e32 v134, 16, v239
	v_and_b32_e32 v137, 0xffff0000, v240
	v_lshlrev_b32_e32 v136, 16, v240
	v_and_b32_e32 v139, 0xffff0000, v241
	v_lshlrev_b32_e32 v138, 16, v241
	v_max_f32_e32 v132, 0xda24260, v132
	v_max_f32_e32 v133, 0xda24260, v133
	v_max_f32_e32 v134, 0xda24260, v134
	v_max_f32_e32 v135, 0xda24260, v135
	v_max_f32_e32 v136, 0xda24260, v136
	v_max_f32_e32 v137, 0xda24260, v137
	v_max_f32_e32 v138, 0xda24260, v138
	v_max_f32_e32 v139, 0xda24260, v139
	v_rcp_f32_e32 v132, v132
	v_rcp_f32_e32 v133, v133
	v_rcp_f32_e32 v134, v134
	v_rcp_f32_e32 v135, v135
	v_rcp_f32_e32 v136, v136
	v_rcp_f32_e32 v137, v137
	v_rcp_f32_e32 v138, v138
	v_rcp_f32_e32 v139, v139
	v_and_b32_e32 v147, 0xffff0000, v230
	v_lshlrev_b32_e32 v146, 16, v230
	v_and_b32_e32 v149, 0xffff0000, v231
	v_lshlrev_b32_e32 v148, 16, v231
	v_and_b32_e32 v151, 0xffff0000, v232
	v_lshlrev_b32_e32 v150, 16, v232
	v_and_b32_e32 v153, 0xffff0000, v233
	v_lshlrev_b32_e32 v152, 16, v233
	v_pk_mul_f32 v[132:133], v[132:133], v[146:147]
	v_pk_mul_f32 v[134:135], v[134:135], v[148:149]
	v_pk_mul_f32 v[136:137], v[136:137], v[150:151]
	v_pk_mul_f32 v[138:139], v[138:139], v[152:153]
	v_pk_mul_f32 v[8:9], v[8:9], v[132:133]
	v_pk_mul_f32 v[10:11], v[10:11], v[134:135]
	v_pk_mul_f32 v[4:5], v[4:5], v[136:137]
	v_pk_mul_f32 v[6:7], v[6:7], v[138:139]
	s_branch .LBB0_1378
